# compressed-branch general path: validity test is one literal compare per element instead of recomputing the distance
# baseline (speedup 1.0000x reference)
; #define LAS __attribute__((address_space(3)))
; #define MFMA16(a, b, c) __builtin_amdgcn_mfma_f32_16x16x32_bf16(a, b, c, 0, 0, 0)
; __device__ __forceinline__ float ex2(float x) { return __builtin_amdgcn_exp2f(x); }
; __device__ __forceinline__ void qk_scores(const KFrag& f, const LAS bf16_t* qf, f32x4 (&sc)[4]) {
;     const f32x4 z4 = {0.f, 0.f, 0.f, 0.f};
;     const bf16x8 aq0 = *(const LAS bf16x8*)qf, aq1 = *(const LAS bf16x8*)(qf + 512);
; #pragma unroll
;     for (int cc = 0; cc < 4; ++cc) { sc[cc] = MFMA16(aq0, f.k[cc][0], z4); sc[cc] = MFMA16(aq1, f.k[cc][1], sc[cc]); }
; }
; __device__ __forceinline__ void cmp_sm1(const f32x4 (&sc)[4], int gr, int t0, const LAS float* bt, float (&ls)[4], int r16) {
; #pragma unroll
;     for (int cc = 0; cc < 4; ++cc) {
;         const int cend = (gr * 64 + cc * 16 + r16) * 16 + 31;
; #pragma unroll
;         for (int i = 0; i < 4; ++i) { const int dist = t0 + i - cend; ls[i] += dist >= 0 ? ex2(sc[cc][i] + bt[clampd(dist)]) : 0.f; }
;     }
; }
.Lcmp_gen_q0p1:
	s_nop 1
	s_waitcnt lgkmcnt(7)
	v_mfma_f32_16x16x32_bf16 v[18:21], v[50:53], v[34:37], 0
	s_waitcnt lgkmcnt(6)
	v_mfma_f32_16x16x32_bf16 v[18:21], v[54:57], v[38:41], v[18:21]
	s_waitcnt lgkmcnt(5)
	v_mfma_f32_16x16x32_bf16 v[22:25], v[58:61], v[34:37], 0
	s_waitcnt lgkmcnt(4)
	v_mfma_f32_16x16x32_bf16 v[22:25], v[62:65], v[38:41], v[22:25]
	s_waitcnt lgkmcnt(3)
	v_mfma_f32_16x16x32_bf16 v[26:29], v[66:69], v[34:37], 0
	s_waitcnt lgkmcnt(2)
	v_mfma_f32_16x16x32_bf16 v[26:29], v[70:73], v[38:41], v[26:29]
	s_waitcnt lgkmcnt(1)
	v_mfma_f32_16x16x32_bf16 v[30:33], v[74:77], v[34:37], 0
	s_waitcnt lgkmcnt(0)
	v_mfma_f32_16x16x32_bf16 v[30:33], v[78:81], v[38:41], v[30:33]
	s_lshl_b32 s0, s57, 10
	v_subrev_u32_e32 v224, s0, v99
	v_add_u32_e32 v232, 0x0, v224
	v_min_u32_e32 v232, 0x400, v232
	v_lshl_add_u32 v232, v232, 2, v173
	ds_read_b32 v216, v232
	v_add_u32_e32 v232, 0xfffffff0, v224
	v_min_u32_e32 v232, 0x400, v232
	v_lshl_add_u32 v232, v232, 2, v173
	ds_read_b32 v217, v232
	v_add_u32_e32 v232, 0xffffffe0, v224
	v_min_u32_e32 v232, 0x400, v232
	v_lshl_add_u32 v232, v232, 2, v173
	ds_read_b32 v218, v232
	v_add_u32_e32 v232, 0xffffffd0, v224
	v_min_u32_e32 v232, 0x400, v232
	v_lshl_add_u32 v232, v232, 2, v173
	ds_read_b32 v219, v232
	v_add_u32_e32 v232, 0xffffffc0, v224
	v_min_u32_e32 v232, 0x400, v232
	v_lshl_add_u32 v232, v232, 2, v173
	ds_read_b32 v220, v232
	v_add_u32_e32 v232, 0xffffffb0, v224
	v_min_u32_e32 v232, 0x400, v232
	v_lshl_add_u32 v232, v232, 2, v173
	ds_read_b32 v221, v232
	v_add_u32_e32 v232, 0xffffffa0, v224
	v_min_u32_e32 v232, 0x400, v232
	v_lshl_add_u32 v232, v232, 2, v173
	ds_read_b32 v222, v232
	v_add_u32_e32 v232, 0xffffff90, v224
	v_min_u32_e32 v232, 0x400, v232
	v_lshl_add_u32 v232, v232, 2, v173
	ds_read_b32 v223, v232
	s_waitcnt lgkmcnt(7)
	v_cmp_le_i32_e32 vcc, 0, v224
	s_nop 1
	v_cndmask_b32_e32 v216, v252, v216, vcc
	v_add_f32_e32 v18, v18, v216
	s_waitcnt lgkmcnt(6)
	v_cmp_le_i32_e32 vcc, 16, v224
	s_nop 1
	v_cndmask_b32_e32 v217, v252, v217, vcc
	v_add_f32_e32 v19, v19, v217
	s_waitcnt lgkmcnt(5)
	v_cmp_le_i32_e32 vcc, 32, v224
	s_nop 1
	v_cndmask_b32_e32 v218, v252, v218, vcc
	v_add_f32_e32 v20, v20, v218
	s_waitcnt lgkmcnt(4)
	v_cmp_le_i32_e32 vcc, 48, v224
	s_nop 1
	v_cndmask_b32_e32 v219, v252, v219, vcc
	v_add_f32_e32 v21, v21, v219
	s_waitcnt lgkmcnt(3)
	v_cmp_le_i32_e32 vcc, 64, v224
	s_nop 1
	v_cndmask_b32_e32 v220, v252, v220, vcc
	v_add_f32_e32 v22, v22, v220
	s_waitcnt lgkmcnt(2)
	v_cmp_le_i32_e32 vcc, 0x50, v224
	s_nop 1
	v_cndmask_b32_e32 v221, v252, v221, vcc
	v_add_f32_e32 v23, v23, v221
	s_waitcnt lgkmcnt(1)
	v_cmp_le_i32_e32 vcc, 0x60, v224
	s_nop 1
	v_cndmask_b32_e32 v222, v252, v222, vcc
	v_add_f32_e32 v24, v24, v222
	s_waitcnt lgkmcnt(0)
	v_cmp_le_i32_e32 vcc, 0x70, v224
	s_nop 1
	v_cndmask_b32_e32 v223, v252, v223, vcc
	v_add_f32_e32 v25, v25, v223
	v_add_u32_e32 v232, 0xfffffe00, v224
	v_min_u32_e32 v232, 0x400, v232
	v_lshl_add_u32 v232, v232, 2, v173
	ds_read_b32 v216, v232
	v_add_u32_e32 v232, 0xfffffdf0, v224
	v_min_u32_e32 v232, 0x400, v232
	v_lshl_add_u32 v232, v232, 2, v173
	ds_read_b32 v217, v232
	v_add_u32_e32 v232, 0xfffffde0, v224
	v_min_u32_e32 v232, 0x400, v232
	v_lshl_add_u32 v232, v232, 2, v173
	ds_read_b32 v218, v232
	v_add_u32_e32 v232, 0xfffffdd0, v224
	v_min_u32_e32 v232, 0x400, v232
	v_lshl_add_u32 v232, v232, 2, v173
	ds_read_b32 v219, v232
	v_add_u32_e32 v232, 0xfffffdc0, v224
	v_min_u32_e32 v232, 0x400, v232
	v_lshl_add_u32 v232, v232, 2, v173
	ds_read_b32 v220, v232
	v_add_u32_e32 v232, 0xfffffdb0, v224
	v_min_u32_e32 v232, 0x400, v232
	v_lshl_add_u32 v232, v232, 2, v173
	ds_read_b32 v221, v232
	v_add_u32_e32 v232, 0xfffffda0, v224
	v_min_u32_e32 v232, 0x400, v232
	v_lshl_add_u32 v232, v232, 2, v173
	ds_read_b32 v222, v232
	v_add_u32_e32 v232, 0xfffffd90, v224
	v_min_u32_e32 v232, 0x400, v232
	v_lshl_add_u32 v232, v232, 2, v173
	ds_read_b32 v223, v232
	s_waitcnt lgkmcnt(7)
	v_cmp_le_i32_e32 vcc, 0x200, v224
	s_nop 1
	v_cndmask_b32_e32 v216, v252, v216, vcc
	v_add_f32_e32 v26, v26, v216
	s_waitcnt lgkmcnt(6)
	v_cmp_le_i32_e32 vcc, 0x210, v224
	s_nop 1
	v_cndmask_b32_e32 v217, v252, v217, vcc
	v_add_f32_e32 v27, v27, v217
	s_waitcnt lgkmcnt(5)
	v_cmp_le_i32_e32 vcc, 0x220, v224
	s_nop 1
	v_cndmask_b32_e32 v218, v252, v218, vcc
	v_add_f32_e32 v28, v28, v218
	s_waitcnt lgkmcnt(4)
	v_cmp_le_i32_e32 vcc, 0x230, v224
	s_nop 1
	v_cndmask_b32_e32 v219, v252, v219, vcc
	v_add_f32_e32 v29, v29, v219
	s_waitcnt lgkmcnt(3)
	v_cmp_le_i32_e32 vcc, 0x240, v224
	s_nop 1
	v_cndmask_b32_e32 v220, v252, v220, vcc
	v_add_f32_e32 v30, v30, v220
	s_waitcnt lgkmcnt(2)
	v_cmp_le_i32_e32 vcc, 0x250, v224
	s_nop 1
	v_cndmask_b32_e32 v221, v252, v221, vcc
	v_add_f32_e32 v31, v31, v221
	s_waitcnt lgkmcnt(1)
	v_cmp_le_i32_e32 vcc, 0x260, v224
	s_nop 1
	v_cndmask_b32_e32 v222, v252, v222, vcc
	v_add_f32_e32 v32, v32, v222
	s_waitcnt lgkmcnt(0)
	v_cmp_le_i32_e32 vcc, 0x270, v224
	s_nop 1
	v_cndmask_b32_e32 v223, v252, v223, vcc
	v_add_f32_e32 v33, v33, v223
	v_exp_f32_e32 v18, v18
	v_exp_f32_e32 v19, v19
	v_exp_f32_e32 v20, v20
	v_exp_f32_e32 v21, v21
	v_exp_f32_e32 v22, v22
	v_exp_f32_e32 v23, v23
	v_exp_f32_e32 v24, v24
	v_exp_f32_e32 v25, v25
	v_exp_f32_e32 v26, v26
	v_exp_f32_e32 v27, v27
	v_exp_f32_e32 v28, v28
	v_exp_f32_e32 v29, v29
	v_exp_f32_e32 v30, v30
	v_exp_f32_e32 v31, v31
	v_exp_f32_e32 v32, v32
	v_exp_f32_e32 v33, v33
	v_add_f32_e32 v18, v18, v19
	v_add_f32_e32 v20, v20, v21
	v_add_f32_e32 v22, v22, v23
	v_add_f32_e32 v24, v24, v25
	v_add_f32_e32 v26, v26, v27
	v_add_f32_e32 v28, v28, v29
	v_add_f32_e32 v30, v30, v31
	v_add_f32_e32 v32, v32, v33
	v_add_f32_e32 v18, v18, v20
	v_add_f32_e32 v22, v22, v24
	v_add_f32_e32 v26, v26, v28
	v_add_f32_e32 v30, v30, v32
	v_add_f32_e32 v18, v18, v22
	v_add_f32_e32 v26, v26, v30
	v_add_f32_e32 v18, v18, v26
	v_add_f32_e32 v170, v170, v18
	s_branch .Lcmp_tail_q0p1

; #define LAS __attribute__((address_space(3)))
; #define MFMA16(a, b, c) __builtin_amdgcn_mfma_f32_16x16x32_bf16(a, b, c, 0, 0, 0)
; __device__ __forceinline__ bf16_t tobf(float x) { return (bf16_t)pk2(x, 0.f); }
; __device__ __forceinline__ float ex2(float x) { return __builtin_amdgcn_exp2f(x); }
; __device__ __forceinline__ void qk_scores(const KFrag& f, const LAS bf16_t* qf, f32x4 (&sc)[4]) {
;     const f32x4 z4 = {0.f, 0.f, 0.f, 0.f};
;     const bf16x8 aq0 = *(const LAS bf16x8*)qf, aq1 = *(const LAS bf16x8*)(qf + 512);
; #pragma unroll
;     for (int cc = 0; cc < 4; ++cc) { sc[cc] = MFMA16(aq0, f.k[cc][0], z4); sc[cc] = MFMA16(aq1, f.k[cc][1], sc[cc]); }
; }
; __device__ __forceinline__ void cmp_sm2(const f32x4 (&sc)[4], int gr, int t0, const LAS float* bt, const float (&inv)[4], LAS bf16_t* Pb, LAS float* psum, int r16, int q4) {
; #pragma unroll
;     for (int cc = 0; cc < 4; ++cc) {
;         const int kk = gr * 64 + cc * 16 + r16, cend = kk * 16 + 31;
; #pragma unroll
;         for (int i = 0; i < 4; ++i) { const int dist = t0 + i - cend; float p = dist >= 0 ? ex2(sc[cc][i] + bt[clampd(dist)]) * inv[i] : 0.f;
;             Pb[(4 * q4 + i) * 72 + cc * 16 + r16] = tobf(p); p += __shfl_xor(p, 16); p += __shfl_xor(p, 32); if (q4 == 0) psum[i * 512 + kk] = p; }
.Lcmp_gen_q0p2:
	s_nop 1
	s_waitcnt lgkmcnt(7)
	v_mfma_f32_16x16x32_bf16 v[18:21], v[50:53], v[34:37], 0
	s_waitcnt lgkmcnt(6)
	v_mfma_f32_16x16x32_bf16 v[18:21], v[54:57], v[38:41], v[18:21]
	s_waitcnt lgkmcnt(5)
	v_mfma_f32_16x16x32_bf16 v[22:25], v[58:61], v[34:37], 0
	s_waitcnt lgkmcnt(4)
	v_mfma_f32_16x16x32_bf16 v[22:25], v[62:65], v[38:41], v[22:25]
	s_waitcnt lgkmcnt(3)
	v_mfma_f32_16x16x32_bf16 v[26:29], v[66:69], v[34:37], 0
	s_waitcnt lgkmcnt(2)
	v_mfma_f32_16x16x32_bf16 v[26:29], v[70:73], v[38:41], v[26:29]
	s_waitcnt lgkmcnt(1)
	v_mfma_f32_16x16x32_bf16 v[30:33], v[74:77], v[34:37], 0
	s_waitcnt lgkmcnt(0)
	v_mfma_f32_16x16x32_bf16 v[30:33], v[78:81], v[38:41], v[30:33]
	s_lshl_b32 s0, s57, 10
	v_subrev_u32_e32 v224, s0, v99
	v_add_u32_e32 v232, 0x0, v224
	v_min_u32_e32 v232, 0x400, v232
	v_lshl_add_u32 v232, v232, 2, v173
	ds_read_b32 v216, v232
	v_add_u32_e32 v232, 0xfffffff0, v224
	v_min_u32_e32 v232, 0x400, v232
	v_lshl_add_u32 v232, v232, 2, v173
	ds_read_b32 v217, v232
	v_add_u32_e32 v232, 0xffffffe0, v224
	v_min_u32_e32 v232, 0x400, v232
	v_lshl_add_u32 v232, v232, 2, v173
	ds_read_b32 v218, v232
	v_add_u32_e32 v232, 0xffffffd0, v224
	v_min_u32_e32 v232, 0x400, v232
	v_lshl_add_u32 v232, v232, 2, v173
	ds_read_b32 v219, v232
	v_add_u32_e32 v232, 0xffffffc0, v224
	v_min_u32_e32 v232, 0x400, v232
	v_lshl_add_u32 v232, v232, 2, v173
	ds_read_b32 v220, v232
	v_add_u32_e32 v232, 0xffffffb0, v224
	v_min_u32_e32 v232, 0x400, v232
	v_lshl_add_u32 v232, v232, 2, v173
	ds_read_b32 v221, v232
	v_add_u32_e32 v232, 0xffffffa0, v224
	v_min_u32_e32 v232, 0x400, v232
	v_lshl_add_u32 v232, v232, 2, v173
	ds_read_b32 v222, v232
	v_add_u32_e32 v232, 0xffffff90, v224
	v_min_u32_e32 v232, 0x400, v232
	v_lshl_add_u32 v232, v232, 2, v173
	ds_read_b32 v223, v232
	s_waitcnt lgkmcnt(7)
	v_cmp_le_i32_e32 vcc, 0, v224
	s_nop 1
	v_cndmask_b32_e32 v216, v252, v216, vcc
	v_add_f32_e32 v18, v18, v216
	s_waitcnt lgkmcnt(6)
	v_cmp_le_i32_e32 vcc, 16, v224
	s_nop 1
	v_cndmask_b32_e32 v217, v252, v217, vcc
	v_add_f32_e32 v19, v19, v217
	s_waitcnt lgkmcnt(5)
	v_cmp_le_i32_e32 vcc, 32, v224
	s_nop 1
	v_cndmask_b32_e32 v218, v252, v218, vcc
	v_add_f32_e32 v20, v20, v218
	s_waitcnt lgkmcnt(4)
	v_cmp_le_i32_e32 vcc, 48, v224
	s_nop 1
	v_cndmask_b32_e32 v219, v252, v219, vcc
	v_add_f32_e32 v21, v21, v219
	s_waitcnt lgkmcnt(3)
	v_cmp_le_i32_e32 vcc, 64, v224
	s_nop 1
	v_cndmask_b32_e32 v220, v252, v220, vcc
	v_add_f32_e32 v22, v22, v220
	s_waitcnt lgkmcnt(2)
	v_cmp_le_i32_e32 vcc, 0x50, v224
	s_nop 1
	v_cndmask_b32_e32 v221, v252, v221, vcc
	v_add_f32_e32 v23, v23, v221
	s_waitcnt lgkmcnt(1)
	v_cmp_le_i32_e32 vcc, 0x60, v224
	s_nop 1
	v_cndmask_b32_e32 v222, v252, v222, vcc
	v_add_f32_e32 v24, v24, v222
	s_waitcnt lgkmcnt(0)
	v_cmp_le_i32_e32 vcc, 0x70, v224
	s_nop 1
	v_cndmask_b32_e32 v223, v252, v223, vcc
	v_add_f32_e32 v25, v25, v223
	v_add_u32_e32 v232, 0xfffffe00, v224
	v_min_u32_e32 v232, 0x400, v232
	v_lshl_add_u32 v232, v232, 2, v173
	ds_read_b32 v216, v232
	v_add_u32_e32 v232, 0xfffffdf0, v224
	v_min_u32_e32 v232, 0x400, v232
	v_lshl_add_u32 v232, v232, 2, v173
	ds_read_b32 v217, v232
	v_add_u32_e32 v232, 0xfffffde0, v224
	v_min_u32_e32 v232, 0x400, v232
	v_lshl_add_u32 v232, v232, 2, v173
	ds_read_b32 v218, v232
	v_add_u32_e32 v232, 0xfffffdd0, v224
	v_min_u32_e32 v232, 0x400, v232
	v_lshl_add_u32 v232, v232, 2, v173
	ds_read_b32 v219, v232
	v_add_u32_e32 v232, 0xfffffdc0, v224
	v_min_u32_e32 v232, 0x400, v232
	v_lshl_add_u32 v232, v232, 2, v173
	ds_read_b32 v220, v232
	v_add_u32_e32 v232, 0xfffffdb0, v224
	v_min_u32_e32 v232, 0x400, v232
	v_lshl_add_u32 v232, v232, 2, v173
	ds_read_b32 v221, v232
	v_add_u32_e32 v232, 0xfffffda0, v224
	v_min_u32_e32 v232, 0x400, v232
	v_lshl_add_u32 v232, v232, 2, v173
	ds_read_b32 v222, v232
	v_add_u32_e32 v232, 0xfffffd90, v224
	v_min_u32_e32 v232, 0x400, v232
	v_lshl_add_u32 v232, v232, 2, v173
	ds_read_b32 v223, v232
	s_waitcnt lgkmcnt(7)
	v_cmp_le_i32_e32 vcc, 0x200, v224
	s_nop 1
	v_cndmask_b32_e32 v216, v252, v216, vcc
	v_add_f32_e32 v26, v26, v216
	s_waitcnt lgkmcnt(6)
	v_cmp_le_i32_e32 vcc, 0x210, v224
	s_nop 1
	v_cndmask_b32_e32 v217, v252, v217, vcc
	v_add_f32_e32 v27, v27, v217
	s_waitcnt lgkmcnt(5)
	v_cmp_le_i32_e32 vcc, 0x220, v224
	s_nop 1
	v_cndmask_b32_e32 v218, v252, v218, vcc
	v_add_f32_e32 v28, v28, v218
	s_waitcnt lgkmcnt(4)
	v_cmp_le_i32_e32 vcc, 0x230, v224
	s_nop 1
	v_cndmask_b32_e32 v219, v252, v219, vcc
	v_add_f32_e32 v29, v29, v219
	s_waitcnt lgkmcnt(3)
	v_cmp_le_i32_e32 vcc, 0x240, v224
	s_nop 1
	v_cndmask_b32_e32 v220, v252, v220, vcc
	v_add_f32_e32 v30, v30, v220
	s_waitcnt lgkmcnt(2)
	v_cmp_le_i32_e32 vcc, 0x250, v224
	s_nop 1
	v_cndmask_b32_e32 v221, v252, v221, vcc
	v_add_f32_e32 v31, v31, v221
	s_waitcnt lgkmcnt(1)
	v_cmp_le_i32_e32 vcc, 0x260, v224
	s_nop 1
	v_cndmask_b32_e32 v222, v252, v222, vcc
	v_add_f32_e32 v32, v32, v222
	s_waitcnt lgkmcnt(0)
; #define LAS __attribute__((address_space(3)))
; #define CBAR() asm volatile("" ::: "memory")
; #define MFMA16(a, b, c) __builtin_amdgcn_mfma_f32_16x16x32_bf16(a, b, c, 0, 0, 0)
; __device__ __forceinline__ bf16_t tobf(float x) { return (bf16_t)pk2(x, 0.f); }
; __device__ __forceinline__ float ex2(float x) { return __builtin_amdgcn_exp2f(x); }
; __device__ __forceinline__ void pv_step(const VFrag& f, f32x4 (&o)[4], const LAS bf16_t* Pb, int r16, int q4) {
;     CBAR();
; #pragma unroll
;     for (int ks = 0; ks < 2; ++ks) { const bf16x8 aP = *(const LAS bf16x8*)(Pb + r16 * 72 + ks * 32 + q4 * 8);
; #pragma unroll
;         for (int nt = 0; nt < 4; ++nt) o[nt] = MFMA16(aP, f.v[ks][nt], o[nt]); }
;     CBAR();
; }
; __device__ __forceinline__ void cmp_sm2(const f32x4 (&sc)[4], int gr, int t0, const LAS float* bt, const float (&inv)[4], LAS bf16_t* Pb, LAS float* psum, int r16, int q4) {
; #pragma unroll
;     for (int cc = 0; cc < 4; ++cc) {
;         const int kk = gr * 64 + cc * 16 + r16, cend = kk * 16 + 31;
; #pragma unroll
;         for (int i = 0; i < 4; ++i) { const int dist = t0 + i - cend; float p = dist >= 0 ? ex2(sc[cc][i] + bt[clampd(dist)]) * inv[i] : 0.f;
;             Pb[(4 * q4 + i) * 72 + cc * 16 + r16] = tobf(p); p += __shfl_xor(p, 16); p += __shfl_xor(p, 32); if (q4 == 0) psum[i * 512 + kk] = p; }
;     }
; }
	v_cmp_le_i32_e32 vcc, 0x270, v224
	s_nop 1
	v_cndmask_b32_e32 v223, v252, v223, vcc
	v_add_f32_e32 v33, v33, v223
	s_cmp_eq_u32 s75, 1
	s_cselect_b32 s0, s95, s94
	s_cmp_eq_u32 s75, 2
	s_cselect_b32 s0, s46, s0
	v_add_u32_e32 v179, s0, v177
	v_add_u32_e32 v226, v179, v178
	ds_read_b128 v[82:85], v179 offset:0
	ds_read_b128 v[86:89], v226 offset:0
	ds_read_b128 v[90:93], v179 offset:2048
	ds_read_b128 v[94:97], v226 offset:2048
	ds_read_b128 v[236:239], v179 offset:4096
	ds_read_b128 v[240:243], v226 offset:4096
	ds_read_b128 v[244:247], v179 offset:6144
	ds_read_b128 v[248:251], v226 offset:6144
	v_exp_f32_e32 v18, v18
	v_exp_f32_e32 v19, v19
	v_exp_f32_e32 v20, v20
	v_exp_f32_e32 v21, v21
	v_exp_f32_e32 v22, v22
	v_exp_f32_e32 v23, v23
	v_exp_f32_e32 v24, v24
	v_exp_f32_e32 v25, v25
	v_exp_f32_e32 v26, v26
	v_exp_f32_e32 v27, v27
	v_exp_f32_e32 v28, v28
	v_exp_f32_e32 v29, v29
	v_exp_f32_e32 v30, v30
	v_exp_f32_e32 v31, v31
	v_exp_f32_e32 v32, v32
	v_exp_f32_e32 v33, v33
	v_mul_f32_e32 v18, v18, v171
	v_mul_f32_e32 v19, v19, v171
	v_mul_f32_e32 v20, v20, v171
	v_mul_f32_e32 v21, v21, v171
	v_mul_f32_e32 v22, v22, v171
	v_mul_f32_e32 v23, v23, v171
	v_mul_f32_e32 v24, v24, v171
	v_mul_f32_e32 v25, v25, v171
	v_mul_f32_e32 v26, v26, v171
	v_mul_f32_e32 v27, v27, v171
	v_mul_f32_e32 v28, v28, v171
	v_mul_f32_e32 v29, v29, v171
	v_mul_f32_e32 v30, v30, v171
	v_mul_f32_e32 v31, v31, v171
	v_mul_f32_e32 v32, v32, v171
	v_mul_f32_e32 v33, v33, v171
	v_add_f32_dpp v50, v18, v18 row_shr:4 row_mask:0xf bank_mask:0xf
	v_add_f32_dpp v51, v19, v19 row_shr:4 row_mask:0xf bank_mask:0xf
	v_add_f32_dpp v52, v20, v20 row_shr:4 row_mask:0xf bank_mask:0xf
	v_add_f32_dpp v53, v21, v21 row_shr:4 row_mask:0xf bank_mask:0xf
	v_add_f32_dpp v54, v22, v22 row_shr:4 row_mask:0xf bank_mask:0xf
	v_add_f32_dpp v55, v23, v23 row_shr:4 row_mask:0xf bank_mask:0xf
	v_add_f32_dpp v56, v24, v24 row_shr:4 row_mask:0xf bank_mask:0xf
	v_add_f32_dpp v57, v25, v25 row_shr:4 row_mask:0xf bank_mask:0xf
	v_add_f32_dpp v58, v26, v26 row_shr:4 row_mask:0xf bank_mask:0xf
	v_add_f32_dpp v59, v27, v27 row_shr:4 row_mask:0xf bank_mask:0xf
	v_add_f32_dpp v60, v28, v28 row_shr:4 row_mask:0xf bank_mask:0xf
	v_add_f32_dpp v61, v29, v29 row_shr:4 row_mask:0xf bank_mask:0xf
	v_add_f32_dpp v62, v30, v30 row_shr:4 row_mask:0xf bank_mask:0xf
	v_add_f32_dpp v63, v31, v31 row_shr:4 row_mask:0xf bank_mask:0xf
	v_add_f32_dpp v64, v32, v32 row_shr:4 row_mask:0xf bank_mask:0xf
	v_add_f32_dpp v65, v33, v33 row_shr:4 row_mask:0xf bank_mask:0xf
	v_add_f32_dpp v50, v50, v50 row_shr:8 row_mask:0xf bank_mask:0xf
	v_add_f32_dpp v51, v51, v51 row_shr:8 row_mask:0xf bank_mask:0xf
	v_add_f32_dpp v52, v52, v52 row_shr:8 row_mask:0xf bank_mask:0xf
	v_add_f32_dpp v53, v53, v53 row_shr:8 row_mask:0xf bank_mask:0xf
	v_add_f32_dpp v54, v54, v54 row_shr:8 row_mask:0xf bank_mask:0xf
	v_add_f32_dpp v55, v55, v55 row_shr:8 row_mask:0xf bank_mask:0xf
	v_add_f32_dpp v56, v56, v56 row_shr:8 row_mask:0xf bank_mask:0xf
	v_add_f32_dpp v57, v57, v57 row_shr:8 row_mask:0xf bank_mask:0xf
	v_add_f32_dpp v58, v58, v58 row_shr:8 row_mask:0xf bank_mask:0xf
	v_add_f32_dpp v59, v59, v59 row_shr:8 row_mask:0xf bank_mask:0xf
	v_add_f32_dpp v60, v60, v60 row_shr:8 row_mask:0xf bank_mask:0xf
	v_add_f32_dpp v61, v61, v61 row_shr:8 row_mask:0xf bank_mask:0xf
	v_add_f32_dpp v62, v62, v62 row_shr:8 row_mask:0xf bank_mask:0xf
	v_add_f32_dpp v63, v63, v63 row_shr:8 row_mask:0xf bank_mask:0xf
	v_add_f32_dpp v64, v64, v64 row_shr:8 row_mask:0xf bank_mask:0xf
	v_add_f32_dpp v65, v65, v65 row_shr:8 row_mask:0xf bank_mask:0xf
	s_lshl_b32 s0, s57, 8
	v_add_u32_e32 v232, s0, v215
	v_cmp_lt_u32_e32 vcc, 11, v98
	s_nop 0
	s_and_saveexec_b64 s[20:21], vcc
	ds_write_b128 v232, v[50:53] offset:0
	ds_write_b128 v232, v[54:57] offset:16
	ds_write_b128 v232, v[58:61] offset:128
	ds_write_b128 v232, v[62:65] offset:144
	s_or_b64 exec, exec, s[20:21]
	v_cvt_pk_bf16_f32 v216, v18, v19
	v_cvt_pk_bf16_f32 v217, v20, v21
	v_cvt_pk_bf16_f32 v218, v22, v23
	v_cvt_pk_bf16_f32 v219, v24, v25
	v_cvt_pk_bf16_f32 v220, v26, v27
	v_cvt_pk_bf16_f32 v221, v28, v29
	v_cvt_pk_bf16_f32 v222, v30, v31
	v_cvt_pk_bf16_f32 v223, v32, v33
	s_waitcnt lgkmcnt(11)
	v_mfma_f32_16x16x32_bf16 v[2:5], v[82:85], v[216:219], v[2:5]
	s_waitcnt lgkmcnt(10)
	v_mfma_f32_16x16x32_bf16 v[2:5], v[86:89], v[220:223], v[2:5]
	s_waitcnt lgkmcnt(9)
	v_mfma_f32_16x16x32_bf16 v[6:9], v[90:93], v[216:219], v[6:9]
	s_waitcnt lgkmcnt(8)
	v_mfma_f32_16x16x32_bf16 v[6:9], v[94:97], v[220:223], v[6:9]
	s_waitcnt lgkmcnt(7)
	v_mfma_f32_16x16x32_bf16 v[10:13], v[236:239], v[216:219], v[10:13]
	s_waitcnt lgkmcnt(6)
	v_mfma_f32_16x16x32_bf16 v[10:13], v[240:243], v[220:223], v[10:13]
	s_waitcnt lgkmcnt(5)
	v_mfma_f32_16x16x32_bf16 v[14:17], v[244:247], v[216:219], v[14:17]
	s_waitcnt lgkmcnt(4)
	v_mfma_f32_16x16x32_bf16 v[14:17], v[248:251], v[220:223], v[14:17]
	s_branch .Lcmp_tail_q0p2

; #define LAS __attribute__((address_space(3)))
; #define MFMA16(a, b, c) __builtin_amdgcn_mfma_f32_16x16x32_bf16(a, b, c, 0, 0, 0)
; __device__ __forceinline__ float ex2(float x) { return __builtin_amdgcn_exp2f(x); }
; __device__ __forceinline__ void qk_scores(const KFrag& f, const LAS bf16_t* qf, f32x4 (&sc)[4]) {
;     const f32x4 z4 = {0.f, 0.f, 0.f, 0.f};
;     const bf16x8 aq0 = *(const LAS bf16x8*)qf, aq1 = *(const LAS bf16x8*)(qf + 512);
; #pragma unroll
;     for (int cc = 0; cc < 4; ++cc) { sc[cc] = MFMA16(aq0, f.k[cc][0], z4); sc[cc] = MFMA16(aq1, f.k[cc][1], sc[cc]); }
; }
; __device__ __forceinline__ void cmp_sm1(const f32x4 (&sc)[4], int gr, int t0, const LAS float* bt, float (&ls)[4], int r16) {
; #pragma unroll
;     for (int cc = 0; cc < 4; ++cc) {
;         const int cend = (gr * 64 + cc * 16 + r16) * 16 + 31;
; #pragma unroll
;         for (int i = 0; i < 4; ++i) { const int dist = t0 + i - cend; ls[i] += dist >= 0 ? ex2(sc[cc][i] + bt[clampd(dist)]) : 0.f; }
;     }
; }
.Lcmp_gen_q1p1:
	s_nop 1
	s_waitcnt lgkmcnt(7)
	v_mfma_f32_16x16x32_bf16 v[18:21], v[50:53], v[42:45], 0
	s_waitcnt lgkmcnt(6)
	v_mfma_f32_16x16x32_bf16 v[18:21], v[54:57], v[46:49], v[18:21]
	s_waitcnt lgkmcnt(5)
	v_mfma_f32_16x16x32_bf16 v[22:25], v[58:61], v[42:45], 0
	s_waitcnt lgkmcnt(4)
	v_mfma_f32_16x16x32_bf16 v[22:25], v[62:65], v[46:49], v[22:25]
	s_waitcnt lgkmcnt(3)
	v_mfma_f32_16x16x32_bf16 v[26:29], v[66:69], v[42:45], 0
	s_waitcnt lgkmcnt(2)
	v_mfma_f32_16x16x32_bf16 v[26:29], v[70:73], v[46:49], v[26:29]
	s_waitcnt lgkmcnt(1)
	v_mfma_f32_16x16x32_bf16 v[30:33], v[74:77], v[42:45], 0
	s_waitcnt lgkmcnt(0)
	v_mfma_f32_16x16x32_bf16 v[30:33], v[78:81], v[46:49], v[30:33]
	s_lshl_b32 s0, s57, 10
	v_subrev_u32_e32 v224, s0, v99
	v_add_u32_e32 v232, 0x0, v224
	v_min_u32_e32 v232, 0x400, v232
	v_lshl_add_u32 v232, v232, 2, v173
	ds_read_b32 v216, v232
	v_add_u32_e32 v232, 0xfffffff0, v224
	v_min_u32_e32 v232, 0x400, v232
	v_lshl_add_u32 v232, v232, 2, v173
	ds_read_b32 v217, v232
	v_add_u32_e32 v232, 0xffffffe0, v224
	v_min_u32_e32 v232, 0x400, v232
	v_lshl_add_u32 v232, v232, 2, v173
	ds_read_b32 v218, v232
	v_add_u32_e32 v232, 0xffffffd0, v224
	v_min_u32_e32 v232, 0x400, v232
	v_lshl_add_u32 v232, v232, 2, v173
	ds_read_b32 v219, v232
	v_add_u32_e32 v232, 0xffffffc0, v224
	v_min_u32_e32 v232, 0x400, v232
	v_lshl_add_u32 v232, v232, 2, v173
	ds_read_b32 v220, v232
	v_add_u32_e32 v232, 0xffffffb0, v224
	v_min_u32_e32 v232, 0x400, v232
	v_lshl_add_u32 v232, v232, 2, v173
	ds_read_b32 v221, v232
	v_add_u32_e32 v232, 0xffffffa0, v224
	v_min_u32_e32 v232, 0x400, v232
	v_lshl_add_u32 v232, v232, 2, v173
	ds_read_b32 v222, v232
	v_add_u32_e32 v232, 0xffffff90, v224
	v_min_u32_e32 v232, 0x400, v232
	v_lshl_add_u32 v232, v232, 2, v173
	ds_read_b32 v223, v232
	s_waitcnt lgkmcnt(7)
	v_cmp_le_i32_e32 vcc, 0, v224
	s_nop 1
	v_cndmask_b32_e32 v216, v252, v216, vcc
	v_add_f32_e32 v18, v18, v216
	s_waitcnt lgkmcnt(6)
	v_cmp_le_i32_e32 vcc, 16, v224
	s_nop 1
	v_cndmask_b32_e32 v217, v252, v217, vcc
	v_add_f32_e32 v19, v19, v217
	s_waitcnt lgkmcnt(5)
	v_cmp_le_i32_e32 vcc, 32, v224
	s_nop 1
	v_cndmask_b32_e32 v218, v252, v218, vcc
	v_add_f32_e32 v20, v20, v218
	s_waitcnt lgkmcnt(4)
	v_cmp_le_i32_e32 vcc, 48, v224
	s_nop 1
	v_cndmask_b32_e32 v219, v252, v219, vcc
	v_add_f32_e32 v21, v21, v219
	s_waitcnt lgkmcnt(3)
	v_cmp_le_i32_e32 vcc, 64, v224
	s_nop 1
	v_cndmask_b32_e32 v220, v252, v220, vcc
	v_add_f32_e32 v22, v22, v220
	s_waitcnt lgkmcnt(2)
	v_cmp_le_i32_e32 vcc, 0x50, v224
	s_nop 1
	v_cndmask_b32_e32 v221, v252, v221, vcc
	v_add_f32_e32 v23, v23, v221
	s_waitcnt lgkmcnt(1)
	v_cmp_le_i32_e32 vcc, 0x60, v224
	s_nop 1
	v_cndmask_b32_e32 v222, v252, v222, vcc
	v_add_f32_e32 v24, v24, v222
	s_waitcnt lgkmcnt(0)
	v_cmp_le_i32_e32 vcc, 0x70, v224
	s_nop 1
	v_cndmask_b32_e32 v223, v252, v223, vcc
	v_add_f32_e32 v25, v25, v223
	v_add_u32_e32 v232, 0xfffffe00, v224
	v_min_u32_e32 v232, 0x400, v232
	v_lshl_add_u32 v232, v232, 2, v173
	ds_read_b32 v216, v232
	v_add_u32_e32 v232, 0xfffffdf0, v224
	v_min_u32_e32 v232, 0x400, v232
	v_lshl_add_u32 v232, v232, 2, v173
	ds_read_b32 v217, v232
	v_add_u32_e32 v232, 0xfffffde0, v224
	v_min_u32_e32 v232, 0x400, v232
	v_lshl_add_u32 v232, v232, 2, v173
	ds_read_b32 v218, v232
	v_add_u32_e32 v232, 0xfffffdd0, v224
	v_min_u32_e32 v232, 0x400, v232
	v_lshl_add_u32 v232, v232, 2, v173
	ds_read_b32 v219, v232
	v_add_u32_e32 v232, 0xfffffdc0, v224
	v_min_u32_e32 v232, 0x400, v232
	v_lshl_add_u32 v232, v232, 2, v173
	ds_read_b32 v220, v232
	v_add_u32_e32 v232, 0xfffffdb0, v224
	v_min_u32_e32 v232, 0x400, v232
	v_lshl_add_u32 v232, v232, 2, v173
	ds_read_b32 v221, v232
	v_add_u32_e32 v232, 0xfffffda0, v224
	v_min_u32_e32 v232, 0x400, v232
	v_lshl_add_u32 v232, v232, 2, v173
	ds_read_b32 v222, v232
	v_add_u32_e32 v232, 0xfffffd90, v224
	v_min_u32_e32 v232, 0x400, v232
	v_lshl_add_u32 v232, v232, 2, v173
	ds_read_b32 v223, v232
	s_waitcnt lgkmcnt(7)
	v_cmp_le_i32_e32 vcc, 0x200, v224
	s_nop 1
	v_cndmask_b32_e32 v216, v252, v216, vcc
	v_add_f32_e32 v26, v26, v216
	s_waitcnt lgkmcnt(6)
	v_cmp_le_i32_e32 vcc, 0x210, v224
	s_nop 1
	v_cndmask_b32_e32 v217, v252, v217, vcc
	v_add_f32_e32 v27, v27, v217
	s_waitcnt lgkmcnt(5)
	v_cmp_le_i32_e32 vcc, 0x220, v224
	s_nop 1
	v_cndmask_b32_e32 v218, v252, v218, vcc
	v_add_f32_e32 v28, v28, v218
	s_waitcnt lgkmcnt(4)
	v_cmp_le_i32_e32 vcc, 0x230, v224
	s_nop 1
	v_cndmask_b32_e32 v219, v252, v219, vcc
	v_add_f32_e32 v29, v29, v219
	s_waitcnt lgkmcnt(3)
	v_cmp_le_i32_e32 vcc, 0x240, v224
	s_nop 1
	v_cndmask_b32_e32 v220, v252, v220, vcc
	v_add_f32_e32 v30, v30, v220
	s_waitcnt lgkmcnt(2)
	v_cmp_le_i32_e32 vcc, 0x250, v224
	s_nop 1
	v_cndmask_b32_e32 v221, v252, v221, vcc
	v_add_f32_e32 v31, v31, v221
	s_waitcnt lgkmcnt(1)
	v_cmp_le_i32_e32 vcc, 0x260, v224
	s_nop 1
	v_cndmask_b32_e32 v222, v252, v222, vcc
	v_add_f32_e32 v32, v32, v222
	s_waitcnt lgkmcnt(0)
	v_cmp_le_i32_e32 vcc, 0x270, v224
	s_nop 1
	v_cndmask_b32_e32 v223, v252, v223, vcc
	v_add_f32_e32 v33, v33, v223
	v_exp_f32_e32 v18, v18
	v_exp_f32_e32 v19, v19
	v_exp_f32_e32 v20, v20
	v_exp_f32_e32 v21, v21
	v_exp_f32_e32 v22, v22
	v_exp_f32_e32 v23, v23
	v_exp_f32_e32 v24, v24
	v_exp_f32_e32 v25, v25
	v_exp_f32_e32 v26, v26
	v_exp_f32_e32 v27, v27
	v_exp_f32_e32 v28, v28
	v_exp_f32_e32 v29, v29
	v_exp_f32_e32 v30, v30
	v_exp_f32_e32 v31, v31
	v_exp_f32_e32 v32, v32
	v_exp_f32_e32 v33, v33
	v_add_f32_e32 v18, v18, v19
	v_add_f32_e32 v20, v20, v21
	v_add_f32_e32 v22, v22, v23
	v_add_f32_e32 v24, v24, v25
	v_add_f32_e32 v26, v26, v27
	v_add_f32_e32 v28, v28, v29
	v_add_f32_e32 v30, v30, v31
	v_add_f32_e32 v32, v32, v33
	v_add_f32_e32 v18, v18, v20
	v_add_f32_e32 v22, v22, v24
	v_add_f32_e32 v26, v26, v28
	v_add_f32_e32 v30, v30, v32
	v_add_f32_e32 v18, v18, v22
	v_add_f32_e32 v26, v26, v30
	v_add_f32_e32 v18, v18, v26
	v_add_f32_e32 v170, v170, v18
	s_branch .Lcmp_tail_q1p1

; #define LAS __attribute__((address_space(3)))
; #define MFMA16(a, b, c) __builtin_amdgcn_mfma_f32_16x16x32_bf16(a, b, c, 0, 0, 0)
; __device__ __forceinline__ bf16_t tobf(float x) { return (bf16_t)pk2(x, 0.f); }
; __device__ __forceinline__ float ex2(float x) { return __builtin_amdgcn_exp2f(x); }
; __device__ __forceinline__ void qk_scores(const KFrag& f, const LAS bf16_t* qf, f32x4 (&sc)[4]) {
;     const f32x4 z4 = {0.f, 0.f, 0.f, 0.f};
;     const bf16x8 aq0 = *(const LAS bf16x8*)qf, aq1 = *(const LAS bf16x8*)(qf + 512);
; #pragma unroll
;     for (int cc = 0; cc < 4; ++cc) { sc[cc] = MFMA16(aq0, f.k[cc][0], z4); sc[cc] = MFMA16(aq1, f.k[cc][1], sc[cc]); }
; }
; __device__ __forceinline__ void cmp_sm2(const f32x4 (&sc)[4], int gr, int t0, const LAS float* bt, const float (&inv)[4], LAS bf16_t* Pb, LAS float* psum, int r16, int q4) {
; #pragma unroll
;     for (int cc = 0; cc < 4; ++cc) {
;         const int kk = gr * 64 + cc * 16 + r16, cend = kk * 16 + 31;
; #pragma unroll
;         for (int i = 0; i < 4; ++i) { const int dist = t0 + i - cend; float p = dist >= 0 ? ex2(sc[cc][i] + bt[clampd(dist)]) * inv[i] : 0.f;
;             Pb[(4 * q4 + i) * 72 + cc * 16 + r16] = tobf(p); p += __shfl_xor(p, 16); p += __shfl_xor(p, 32); if (q4 == 0) psum[i * 512 + kk] = p; }
.Lcmp_gen_q1p2:
	s_nop 1
	s_waitcnt lgkmcnt(7)
	v_mfma_f32_16x16x32_bf16 v[18:21], v[50:53], v[42:45], 0
	s_waitcnt lgkmcnt(6)
	v_mfma_f32_16x16x32_bf16 v[18:21], v[54:57], v[46:49], v[18:21]
	s_waitcnt lgkmcnt(5)
	v_mfma_f32_16x16x32_bf16 v[22:25], v[58:61], v[42:45], 0
	s_waitcnt lgkmcnt(4)
	v_mfma_f32_16x16x32_bf16 v[22:25], v[62:65], v[46:49], v[22:25]
	s_waitcnt lgkmcnt(3)
	v_mfma_f32_16x16x32_bf16 v[26:29], v[66:69], v[42:45], 0
	s_waitcnt lgkmcnt(2)
	v_mfma_f32_16x16x32_bf16 v[26:29], v[70:73], v[46:49], v[26:29]
	s_waitcnt lgkmcnt(1)
	v_mfma_f32_16x16x32_bf16 v[30:33], v[74:77], v[42:45], 0
	s_waitcnt lgkmcnt(0)
	v_mfma_f32_16x16x32_bf16 v[30:33], v[78:81], v[46:49], v[30:33]
	s_lshl_b32 s0, s57, 10
	v_subrev_u32_e32 v224, s0, v99
	v_add_u32_e32 v232, 0x0, v224
	v_min_u32_e32 v232, 0x400, v232
	v_lshl_add_u32 v232, v232, 2, v173
	ds_read_b32 v216, v232
	v_add_u32_e32 v232, 0xfffffff0, v224
	v_min_u32_e32 v232, 0x400, v232
	v_lshl_add_u32 v232, v232, 2, v173
	ds_read_b32 v217, v232
	v_add_u32_e32 v232, 0xffffffe0, v224
	v_min_u32_e32 v232, 0x400, v232
	v_lshl_add_u32 v232, v232, 2, v173
	ds_read_b32 v218, v232
	v_add_u32_e32 v232, 0xffffffd0, v224
	v_min_u32_e32 v232, 0x400, v232
	v_lshl_add_u32 v232, v232, 2, v173
	ds_read_b32 v219, v232
	v_add_u32_e32 v232, 0xffffffc0, v224
	v_min_u32_e32 v232, 0x400, v232
	v_lshl_add_u32 v232, v232, 2, v173
	ds_read_b32 v220, v232
	v_add_u32_e32 v232, 0xffffffb0, v224
	v_min_u32_e32 v232, 0x400, v232
	v_lshl_add_u32 v232, v232, 2, v173
	ds_read_b32 v221, v232
	v_add_u32_e32 v232, 0xffffffa0, v224
	v_min_u32_e32 v232, 0x400, v232
	v_lshl_add_u32 v232, v232, 2, v173
	ds_read_b32 v222, v232
	v_add_u32_e32 v232, 0xffffff90, v224
	v_min_u32_e32 v232, 0x400, v232
	v_lshl_add_u32 v232, v232, 2, v173
	ds_read_b32 v223, v232
	s_waitcnt lgkmcnt(7)
	v_cmp_le_i32_e32 vcc, 0, v224
	s_nop 1
	v_cndmask_b32_e32 v216, v252, v216, vcc
	v_add_f32_e32 v18, v18, v216
	s_waitcnt lgkmcnt(6)
	v_cmp_le_i32_e32 vcc, 16, v224
	s_nop 1
	v_cndmask_b32_e32 v217, v252, v217, vcc
	v_add_f32_e32 v19, v19, v217
	s_waitcnt lgkmcnt(5)
	v_cmp_le_i32_e32 vcc, 32, v224
	s_nop 1
	v_cndmask_b32_e32 v218, v252, v218, vcc
	v_add_f32_e32 v20, v20, v218
	s_waitcnt lgkmcnt(4)
	v_cmp_le_i32_e32 vcc, 48, v224
	s_nop 1
	v_cndmask_b32_e32 v219, v252, v219, vcc
	v_add_f32_e32 v21, v21, v219
	s_waitcnt lgkmcnt(3)
	v_cmp_le_i32_e32 vcc, 64, v224
	s_nop 1
	v_cndmask_b32_e32 v220, v252, v220, vcc
	v_add_f32_e32 v22, v22, v220
	s_waitcnt lgkmcnt(2)
	v_cmp_le_i32_e32 vcc, 0x50, v224
	s_nop 1
	v_cndmask_b32_e32 v221, v252, v221, vcc
	v_add_f32_e32 v23, v23, v221
	s_waitcnt lgkmcnt(1)
	v_cmp_le_i32_e32 vcc, 0x60, v224
	s_nop 1
	v_cndmask_b32_e32 v222, v252, v222, vcc
	v_add_f32_e32 v24, v24, v222
	s_waitcnt lgkmcnt(0)
	v_cmp_le_i32_e32 vcc, 0x70, v224
	s_nop 1
	v_cndmask_b32_e32 v223, v252, v223, vcc
	v_add_f32_e32 v25, v25, v223
	v_add_u32_e32 v232, 0xfffffe00, v224
	v_min_u32_e32 v232, 0x400, v232
	v_lshl_add_u32 v232, v232, 2, v173
	ds_read_b32 v216, v232
	v_add_u32_e32 v232, 0xfffffdf0, v224
	v_min_u32_e32 v232, 0x400, v232
	v_lshl_add_u32 v232, v232, 2, v173
	ds_read_b32 v217, v232
	v_add_u32_e32 v232, 0xfffffde0, v224
	v_min_u32_e32 v232, 0x400, v232
	v_lshl_add_u32 v232, v232, 2, v173
	ds_read_b32 v218, v232
	v_add_u32_e32 v232, 0xfffffdd0, v224
	v_min_u32_e32 v232, 0x400, v232
	v_lshl_add_u32 v232, v232, 2, v173
	ds_read_b32 v219, v232
	v_add_u32_e32 v232, 0xfffffdc0, v224
	v_min_u32_e32 v232, 0x400, v232
	v_lshl_add_u32 v232, v232, 2, v173
	ds_read_b32 v220, v232
	v_add_u32_e32 v232, 0xfffffdb0, v224
	v_min_u32_e32 v232, 0x400, v232
	v_lshl_add_u32 v232, v232, 2, v173
	ds_read_b32 v221, v232
	v_add_u32_e32 v232, 0xfffffda0, v224
	v_min_u32_e32 v232, 0x400, v232
	v_lshl_add_u32 v232, v232, 2, v173
	ds_read_b32 v222, v232
	v_add_u32_e32 v232, 0xfffffd90, v224
	v_min_u32_e32 v232, 0x400, v232
	v_lshl_add_u32 v232, v232, 2, v173
	ds_read_b32 v223, v232
	s_waitcnt lgkmcnt(7)
	v_cmp_le_i32_e32 vcc, 0x200, v224
	s_nop 1
	v_cndmask_b32_e32 v216, v252, v216, vcc
	v_add_f32_e32 v26, v26, v216
	s_waitcnt lgkmcnt(6)
	v_cmp_le_i32_e32 vcc, 0x210, v224
	s_nop 1
	v_cndmask_b32_e32 v217, v252, v217, vcc
	v_add_f32_e32 v27, v27, v217
	s_waitcnt lgkmcnt(5)
	v_cmp_le_i32_e32 vcc, 0x220, v224
	s_nop 1
	v_cndmask_b32_e32 v218, v252, v218, vcc
	v_add_f32_e32 v28, v28, v218
	s_waitcnt lgkmcnt(4)
	v_cmp_le_i32_e32 vcc, 0x230, v224
	s_nop 1
	v_cndmask_b32_e32 v219, v252, v219, vcc
	v_add_f32_e32 v29, v29, v219
	s_waitcnt lgkmcnt(3)
	v_cmp_le_i32_e32 vcc, 0x240, v224
	s_nop 1
	v_cndmask_b32_e32 v220, v252, v220, vcc
	v_add_f32_e32 v30, v30, v220
	s_waitcnt lgkmcnt(2)
	v_cmp_le_i32_e32 vcc, 0x250, v224
	s_nop 1
	v_cndmask_b32_e32 v221, v252, v221, vcc
	v_add_f32_e32 v31, v31, v221
	s_waitcnt lgkmcnt(1)
	v_cmp_le_i32_e32 vcc, 0x260, v224
	s_nop 1
	v_cndmask_b32_e32 v222, v252, v222, vcc
	v_add_f32_e32 v32, v32, v222
	s_waitcnt lgkmcnt(0)
; #define LAS __attribute__((address_space(3)))
; #define CBAR() asm volatile("" ::: "memory")
; #define MFMA16(a, b, c) __builtin_amdgcn_mfma_f32_16x16x32_bf16(a, b, c, 0, 0, 0)
; __device__ __forceinline__ bf16_t tobf(float x) { return (bf16_t)pk2(x, 0.f); }
; __device__ __forceinline__ float ex2(float x) { return __builtin_amdgcn_exp2f(x); }
; __device__ __forceinline__ void pv_step(const VFrag& f, f32x4 (&o)[4], const LAS bf16_t* Pb, int r16, int q4) {
;     CBAR();
; #pragma unroll
;     for (int ks = 0; ks < 2; ++ks) { const bf16x8 aP = *(const LAS bf16x8*)(Pb + r16 * 72 + ks * 32 + q4 * 8);
; #pragma unroll
;         for (int nt = 0; nt < 4; ++nt) o[nt] = MFMA16(aP, f.v[ks][nt], o[nt]); }
;     CBAR();
; }
; __device__ __forceinline__ void cmp_sm2(const f32x4 (&sc)[4], int gr, int t0, const LAS float* bt, const float (&inv)[4], LAS bf16_t* Pb, LAS float* psum, int r16, int q4) {
; #pragma unroll
;     for (int cc = 0; cc < 4; ++cc) {
;         const int kk = gr * 64 + cc * 16 + r16, cend = kk * 16 + 31;
; #pragma unroll
;         for (int i = 0; i < 4; ++i) { const int dist = t0 + i - cend; float p = dist >= 0 ? ex2(sc[cc][i] + bt[clampd(dist)]) * inv[i] : 0.f;
;             Pb[(4 * q4 + i) * 72 + cc * 16 + r16] = tobf(p); p += __shfl_xor(p, 16); p += __shfl_xor(p, 32); if (q4 == 0) psum[i * 512 + kk] = p; }
;     }
; }
	v_cmp_le_i32_e32 vcc, 0x270, v224
	s_nop 1
	v_cndmask_b32_e32 v223, v252, v223, vcc
	v_add_f32_e32 v33, v33, v223
	s_cmp_eq_u32 s75, 1
	s_cselect_b32 s0, s95, s94
	s_cmp_eq_u32 s75, 2
	s_cselect_b32 s0, s46, s0
	v_add_u32_e32 v179, s0, v177
	v_add_u32_e32 v226, v179, v178
	ds_read_b128 v[82:85], v179 offset:0
	ds_read_b128 v[86:89], v226 offset:0
	ds_read_b128 v[90:93], v179 offset:2048
	ds_read_b128 v[94:97], v226 offset:2048
	ds_read_b128 v[236:239], v179 offset:4096
	ds_read_b128 v[240:243], v226 offset:4096
	ds_read_b128 v[244:247], v179 offset:6144
	ds_read_b128 v[248:251], v226 offset:6144
	v_exp_f32_e32 v18, v18
	v_exp_f32_e32 v19, v19
	v_exp_f32_e32 v20, v20
	v_exp_f32_e32 v21, v21
	v_exp_f32_e32 v22, v22
	v_exp_f32_e32 v23, v23
	v_exp_f32_e32 v24, v24
	v_exp_f32_e32 v25, v25
	v_exp_f32_e32 v26, v26
	v_exp_f32_e32 v27, v27
	v_exp_f32_e32 v28, v28
	v_exp_f32_e32 v29, v29
	v_exp_f32_e32 v30, v30
	v_exp_f32_e32 v31, v31
	v_exp_f32_e32 v32, v32
	v_exp_f32_e32 v33, v33
	v_mul_f32_e32 v18, v18, v171
	v_mul_f32_e32 v19, v19, v171
	v_mul_f32_e32 v20, v20, v171
	v_mul_f32_e32 v21, v21, v171
	v_mul_f32_e32 v22, v22, v171
	v_mul_f32_e32 v23, v23, v171
	v_mul_f32_e32 v24, v24, v171
	v_mul_f32_e32 v25, v25, v171
	v_mul_f32_e32 v26, v26, v171
	v_mul_f32_e32 v27, v27, v171
	v_mul_f32_e32 v28, v28, v171
	v_mul_f32_e32 v29, v29, v171
	v_mul_f32_e32 v30, v30, v171
	v_mul_f32_e32 v31, v31, v171
	v_mul_f32_e32 v32, v32, v171
	v_mul_f32_e32 v33, v33, v171
	v_add_f32_dpp v50, v18, v18 row_shr:4 row_mask:0xf bank_mask:0xf
	v_add_f32_dpp v51, v19, v19 row_shr:4 row_mask:0xf bank_mask:0xf
	v_add_f32_dpp v52, v20, v20 row_shr:4 row_mask:0xf bank_mask:0xf
	v_add_f32_dpp v53, v21, v21 row_shr:4 row_mask:0xf bank_mask:0xf
	v_add_f32_dpp v54, v22, v22 row_shr:4 row_mask:0xf bank_mask:0xf
	v_add_f32_dpp v55, v23, v23 row_shr:4 row_mask:0xf bank_mask:0xf
	v_add_f32_dpp v56, v24, v24 row_shr:4 row_mask:0xf bank_mask:0xf
	v_add_f32_dpp v57, v25, v25 row_shr:4 row_mask:0xf bank_mask:0xf
	v_add_f32_dpp v58, v26, v26 row_shr:4 row_mask:0xf bank_mask:0xf
	v_add_f32_dpp v59, v27, v27 row_shr:4 row_mask:0xf bank_mask:0xf
	v_add_f32_dpp v60, v28, v28 row_shr:4 row_mask:0xf bank_mask:0xf
	v_add_f32_dpp v61, v29, v29 row_shr:4 row_mask:0xf bank_mask:0xf
	v_add_f32_dpp v62, v30, v30 row_shr:4 row_mask:0xf bank_mask:0xf
	v_add_f32_dpp v63, v31, v31 row_shr:4 row_mask:0xf bank_mask:0xf
	v_add_f32_dpp v64, v32, v32 row_shr:4 row_mask:0xf bank_mask:0xf
	v_add_f32_dpp v65, v33, v33 row_shr:4 row_mask:0xf bank_mask:0xf
	v_add_f32_dpp v50, v50, v50 row_shr:8 row_mask:0xf bank_mask:0xf
	v_add_f32_dpp v51, v51, v51 row_shr:8 row_mask:0xf bank_mask:0xf
	v_add_f32_dpp v52, v52, v52 row_shr:8 row_mask:0xf bank_mask:0xf
	v_add_f32_dpp v53, v53, v53 row_shr:8 row_mask:0xf bank_mask:0xf
	v_add_f32_dpp v54, v54, v54 row_shr:8 row_mask:0xf bank_mask:0xf
	v_add_f32_dpp v55, v55, v55 row_shr:8 row_mask:0xf bank_mask:0xf
	v_add_f32_dpp v56, v56, v56 row_shr:8 row_mask:0xf bank_mask:0xf
	v_add_f32_dpp v57, v57, v57 row_shr:8 row_mask:0xf bank_mask:0xf
	v_add_f32_dpp v58, v58, v58 row_shr:8 row_mask:0xf bank_mask:0xf
	v_add_f32_dpp v59, v59, v59 row_shr:8 row_mask:0xf bank_mask:0xf
	v_add_f32_dpp v60, v60, v60 row_shr:8 row_mask:0xf bank_mask:0xf
	v_add_f32_dpp v61, v61, v61 row_shr:8 row_mask:0xf bank_mask:0xf
	v_add_f32_dpp v62, v62, v62 row_shr:8 row_mask:0xf bank_mask:0xf
	v_add_f32_dpp v63, v63, v63 row_shr:8 row_mask:0xf bank_mask:0xf
	v_add_f32_dpp v64, v64, v64 row_shr:8 row_mask:0xf bank_mask:0xf
	v_add_f32_dpp v65, v65, v65 row_shr:8 row_mask:0xf bank_mask:0xf
	s_lshl_b32 s0, s57, 8
	v_add_u32_e32 v232, s0, v215
	v_cmp_lt_u32_e32 vcc, 11, v98
	s_nop 0
	s_and_saveexec_b64 s[20:21], vcc
	ds_write_b128 v232, v[50:53] offset:0
	ds_write_b128 v232, v[54:57] offset:16
	ds_write_b128 v232, v[58:61] offset:128
	ds_write_b128 v232, v[62:65] offset:144
	s_or_b64 exec, exec, s[20:21]
	v_cvt_pk_bf16_f32 v216, v18, v19
	v_cvt_pk_bf16_f32 v217, v20, v21
	v_cvt_pk_bf16_f32 v218, v22, v23
	v_cvt_pk_bf16_f32 v219, v24, v25
	v_cvt_pk_bf16_f32 v220, v26, v27
	v_cvt_pk_bf16_f32 v221, v28, v29
	v_cvt_pk_bf16_f32 v222, v30, v31
	v_cvt_pk_bf16_f32 v223, v32, v33
	s_waitcnt lgkmcnt(11)
	v_mfma_f32_16x16x32_bf16 v[2:5], v[82:85], v[216:219], v[2:5]
	s_waitcnt lgkmcnt(10)
	v_mfma_f32_16x16x32_bf16 v[2:5], v[86:89], v[220:223], v[2:5]
	s_waitcnt lgkmcnt(9)
	v_mfma_f32_16x16x32_bf16 v[6:9], v[90:93], v[216:219], v[6:9]
	s_waitcnt lgkmcnt(8)
	v_mfma_f32_16x16x32_bf16 v[6:9], v[94:97], v[220:223], v[6:9]
	s_waitcnt lgkmcnt(7)
	v_mfma_f32_16x16x32_bf16 v[10:13], v[236:239], v[216:219], v[10:13]
	s_waitcnt lgkmcnt(6)
	v_mfma_f32_16x16x32_bf16 v[10:13], v[240:243], v[220:223], v[10:13]
	s_waitcnt lgkmcnt(5)
	v_mfma_f32_16x16x32_bf16 v[14:17], v[244:247], v[216:219], v[14:17]
	s_waitcnt lgkmcnt(4)
	v_mfma_f32_16x16x32_bf16 v[14:17], v[248:251], v[220:223], v[14:17]
	s_branch .Lcmp_tail_q1p2
